# gated-merge -> attention-out seam: grid barrier replaced by per-row-tile counters (producers and consumers of a 256-row tile share an XCD, verified at run time), attention-out context K-slices run as
# speedup vs baseline: 1.0044x; 1.0044x over previous
.LBB0_12:
	s_load_dwordx16 s[12:27], s[0:1], 0x0
	s_add_u32 s2, s62, 0x22f38000
	s_addc_u32 s3, s63, 0
	v_cmp_eq_u32_e32 vcc, 0, v1
	s_waitcnt lgkmcnt(0)
	v_writelane_b32 v251, s12, 0
	s_nop 1
	v_writelane_b32 v251, s13, 1
	v_writelane_b32 v251, s14, 2
	v_writelane_b32 v251, s15, 3
	v_writelane_b32 v251, s16, 4
	v_writelane_b32 v251, s17, 5
	v_writelane_b32 v251, s18, 6
	v_writelane_b32 v251, s19, 7
	v_writelane_b32 v251, s20, 8
	v_writelane_b32 v251, s21, 9
	v_writelane_b32 v251, s22, 10
	v_writelane_b32 v251, s23, 11
	v_writelane_b32 v251, s24, 12
	v_writelane_b32 v251, s25, 13
	v_writelane_b32 v251, s26, 14
	v_writelane_b32 v251, s27, 15
	s_load_dwordx16 s[12:27], s[0:1], 0x40
	s_waitcnt lgkmcnt(0)
	v_writelane_b32 v251, s12, 16
	s_nop 1
	v_writelane_b32 v251, s13, 17
	v_writelane_b32 v251, s14, 18
	v_writelane_b32 v251, s15, 19
	v_writelane_b32 v251, s16, 20
	v_writelane_b32 v251, s17, 21
	v_writelane_b32 v251, s18, 22
	v_writelane_b32 v251, s19, 23
	v_writelane_b32 v251, s20, 24
	v_writelane_b32 v251, s21, 25
	v_writelane_b32 v251, s22, 26
	v_writelane_b32 v251, s23, 27
	v_writelane_b32 v251, s24, 28
	v_writelane_b32 v251, s25, 29
	v_writelane_b32 v251, s26, 30
	v_writelane_b32 v251, s27, 31
	v_writelane_b32 v251, s2, 32
	s_nop 1
	v_writelane_b32 v251, s3, 33
	s_and_saveexec_b64 s[2:3], vcc
	s_cbranch_execz .LBB0_15
	s_add_i32 s6, 0, 0x23ff0
	v_mov_b32_e32 v0, 0
	v_mov_b32_e32 v1, s6
	s_add_i32 s6, 0, 0x23ff4
	s_mov_b64 s[4:5], exec
	ds_write_b32 v1, v0
	v_mov_b32_e32 v1, s6
	ds_write_b32 v1, v0
	v_mbcnt_lo_u32_b32 v0, s4, 0
	v_mbcnt_hi_u32_b32 v0, s5, v0
	v_cmp_eq_u32_e32 vcc, 0, v0
	s_getreg_b32 s6, hwreg(HW_REG_XCC_ID, 0, 4)
	s_and_b64 s[8:9], exec, vcc
	s_mov_b64 exec, s[8:9]
	s_cbranch_execz .LBB0_15
	s_lshl_b32 s6, s6, 8
	s_bcnt1_i32_b64 s4, s[4:5]
	s_and_b32 s6, s6, 0xf00
	v_mov_b32_e32 v1, s4
	v_readlane_b32 s4, v251, 32
	v_mov_b32_e32 v0, s6
	v_readlane_b32 s5, v251, 33
	s_nop 4
	global_atomic_add v0, v1, s[4:5] offset:1024
	s_lshr_b32 s6, s6, 8
	s_add_i32 s6, s6, 1
	s_lshl_b32 s8, s91, 2
	s_add_i32 s8, s8, 15104
	v_mov_b32_e32 v0, s8
	v_mov_b32_e32 v1, s6
	global_store_dword v0, v1, s[4:5]

.Lcvth_done2:
.LBB0_156:
	s_movk_i32 s32, 0x207
	s_mov_b32 s0, 0
	v_writelane_b32 v255, s0, 46
	s_mov_b32 s0, 0
	v_writelane_b32 v255, s0, 49
	s_mov_b32 s0, 2
	v_writelane_b32 v255, s0, 48
	s_mov_b32 s0, 0
	v_writelane_b32 v255, s0, 47
	s_add_u32 s0, s62, 0x22f28000
	s_addc_u32 s1, s63, 0
	v_writelane_b32 v251, s0, 37
	s_waitcnt vmcnt(11)
	v_mbcnt_lo_u32_b32 v0, -1, 0
	s_mov_b32 s89, 1
	v_writelane_b32 v251, s1, 38
	s_add_u32 s0, s62, 0x22f30000
	s_addc_u32 s1, s63, 0
	v_writelane_b32 v251, s0, 39
	s_waitcnt lgkmcnt(0)
	s_movk_i32 s33, 0x3000
	v_mov_b32_e32 v33, 0
	v_writelane_b32 v251, s1, 40
	s_add_u32 s0, s62, 0x1bee0000
	v_writelane_b32 v251, s0, 41
	s_addc_u32 s0, s63, 0
	v_writelane_b32 v251, s0, 42
	s_add_u32 s0, s62, 0x22f38200
	s_addc_u32 s1, s63, 0
	s_add_u32 s2, s62, 0x22f38400
	s_addc_u32 s3, s63, 0
	s_add_u32 s4, s62, 0x22f38500
	s_addc_u32 s5, s63, 0
	s_add_u32 s6, s62, 0x22f38600
	v_writelane_b32 v251, s0, 43
	s_addc_u32 s7, s63, 0
	v_mov_b32_e32 v228, 0x1000
	v_writelane_b32 v251, s1, 44
	s_add_u32 s0, s62, 0x22f38700
	s_addc_u32 s1, s63, 0
	v_writelane_b32 v251, s0, 45
	v_mov_b32_e32 v221, 0x2000
	v_mov_b32_e32 v248, 1
	v_writelane_b32 v251, s1, 46
	s_add_u32 s0, s62, 0x22f38800
	s_addc_u32 s1, s63, 0
	v_writelane_b32 v251, s0, 47
	v_mov_b32_e32 v224, 0x358637bd
	v_mbcnt_hi_u32_b32 v220, -1, v0
	v_writelane_b32 v251, s1, 48
	s_add_u32 s0, s62, 0x22f38900
	s_addc_u32 s1, s63, 0
	v_writelane_b32 v251, s0, 49
	v_mov_b32_e32 v225, 0x42800000
	v_not_b32_e32 v226, 63
	v_writelane_b32 v251, s1, 50
	s_add_u32 s0, s62, 0x22f38a00
	s_addc_u32 s1, s63, 0
	v_writelane_b32 v251, s0, 51
	v_mov_b32_e32 v227, 0x410000
	v_mov_b32_e32 v249, 0x160000
	v_writelane_b32 v251, s1, 52
	s_add_u32 s0, s62, 0x22f38b00
	s_addc_u32 s1, s63, 0
	v_writelane_b32 v251, s0, 53
	s_mov_b32 s94, 0x8200
	s_mov_b32 s66, 0xc2fc0000
	v_writelane_b32 v251, s1, 54
	s_add_u32 s0, s62, 0x22f38c00
	s_addc_u32 s1, s63, 0
	v_writelane_b32 v251, s0, 55
	s_movk_i32 s67, 0xffc0
	s_movk_i32 s88, 0x1000
	v_writelane_b32 v251, s1, 56
	s_add_u32 s0, s62, 0x22f38d00
	s_addc_u32 s1, s63, 0
	v_writelane_b32 v251, s0, 57
	s_mov_b32 s78, 0
	s_mov_b32 s97, 0
	v_writelane_b32 v251, s1, 58
	s_add_u32 s0, s62, 0x22f38e00
	s_addc_u32 s1, s63, 0
	v_writelane_b32 v251, s0, 59
	s_mov_b64 s[34:35], 0x100000
	s_mov_b64 s[68:69], 0x100800
	v_writelane_b32 v251, s1, 60
	s_add_u32 s0, s62, 0x22f38f00
	s_addc_u32 s1, s63, 0
	v_writelane_b32 v251, s0, 61
	s_mov_b64 s[84:85], 0x80
	s_nop 0
	v_writelane_b32 v251, s1, 62
	s_add_u32 s0, s62, 0x22f39000
	s_addc_u32 s1, s63, 0
	v_writelane_b32 v251, s0, 63
	s_nop 1
	v_writelane_b32 v252, s1, 0
	s_add_u32 s0, s62, 0x22f39100
	s_addc_u32 s1, s63, 0
	v_writelane_b32 v252, s0, 1
	s_nop 1
	v_writelane_b32 v252, s1, 2
	s_add_u32 s0, s62, 0x22f39200
	s_addc_u32 s1, s63, 0
	v_writelane_b32 v252, s0, 3
	s_nop 1
	v_writelane_b32 v252, s1, 4
	s_add_u32 s0, s62, 0x22f39300
	s_addc_u32 s1, s63, 0
	v_writelane_b32 v252, s0, 5
	s_nop 1
	v_writelane_b32 v252, s1, 6
	s_add_u32 s0, s62, 0x22f3b400
	s_addc_u32 s1, s63, 0
	s_add_u32 s52, s62, 0x22f3b500
	v_writelane_b32 v252, s0, 7
	s_addc_u32 s53, s63, 0
	s_nop 0
	v_writelane_b32 v252, s1, 8
	s_add_u32 s0, s62, 0x2080000
	s_addc_u32 s1, s63, 0
	v_writelane_b32 v252, s0, 9
	s_nop 1
	v_writelane_b32 v252, s1, 10
	s_add_u32 s0, s62, 0x22f3c000
	s_addc_u32 s1, s63, 0
	s_add_u32 s70, s62, 0x9a60000
	v_writelane_b32 v252, s0, 11
	s_addc_u32 s71, s63, 0
	s_nop 0
	v_writelane_b32 v252, s1, 12
	s_add_u32 s0, s62, 0x8200000
	s_addc_u32 s1, s63, 0
	v_writelane_b32 v252, s0, 13
	s_nop 1
	v_writelane_b32 v252, s1, 14
	s_add_u32 s0, s62, 0x15d60000
	s_addc_u32 s1, s63, 0
	s_add_u32 s92, s62, 0x4100000
	v_writelane_b32 v252, s0, 15
	s_addc_u32 s93, s63, 0
	s_nop 0
	v_writelane_b32 v252, s1, 16
	s_add_u32 s0, s62, 0x19e60000
	s_addc_u32 s1, s63, 0
	v_writelane_b32 v252, s0, 17
	s_nop 1
	v_writelane_b32 v252, s1, 18
	s_add_u32 s0, s62, 0x17de0000
	s_addc_u32 s1, s63, 0
	v_writelane_b32 v252, s0, 19
	s_bitcmp1_b32 s91, 0
	s_nop 0
	v_writelane_b32 v252, s1, 20
	s_cselect_b64 s[0:1], -1, 0
	v_writelane_b32 v252, s0, 21
	s_nop 1
	v_writelane_b32 v252, s1, 22
	s_add_u32 s0, s62, 0x23a3c000
	v_writelane_b32 v252, s0, 23
	s_addc_u32 s0, s63, 0
	v_writelane_b32 v252, s0, 24
	s_add_u32 s0, s62, 0x23abc000
	v_writelane_b32 v252, s0, 25
	v_writelane_b32 v252, s56, 26
	s_addc_u32 s0, s63, 0
	s_add_i32 s80, 0, 0x11000
	v_writelane_b32 v252, s57, 27
	v_writelane_b32 v252, s58, 28
	v_writelane_b32 v252, s59, 29
	v_writelane_b32 v252, s60, 30
	v_writelane_b32 v252, s61, 31
	v_writelane_b32 v252, s62, 32
	v_writelane_b32 v252, s63, 33
	v_writelane_b32 v252, s0, 34
	s_add_i32 s0, 0, 0x23ff0
	v_writelane_b32 v252, s0, 35
	s_add_i32 s0, 0, 0x23ff4
	v_writelane_b32 v252, s0, 36
	s_add_i32 s0, 0, 0x22000
	v_writelane_b32 v252, s0, 37
	v_writelane_b32 v252, s52, 38
	s_mov_b64 s[56:57], s[2:3]
	s_mov_b64 s[58:59], s[4:5]
	v_writelane_b32 v252, s53, 39
	v_writelane_b32 v252, s56, 40
	s_mov_b64 s[60:61], s[6:7]
	s_add_i32 s81, 0, 0x19800
	v_writelane_b32 v252, s57, 41
	v_writelane_b32 v252, s58, 42
	s_nop 1
	v_writelane_b32 v252, s59, 43
	v_writelane_b32 v252, s60, 44
	s_nop 1
	v_writelane_b32 v252, s61, 45
	v_writelane_b32 v252, s91, 46
	v_writelane_b32 v252, s54, 47
	s_nop 1
	v_writelane_b32 v252, s55, 48
	v_writelane_b32 v252, s64, 49
	s_nop 1
	v_writelane_b32 v252, s65, 50

.LBB0_950:
	v_readlane_b32 s0, v251, 36
	s_cmp_lg_u32 s0, 0
	s_cbranch_scc1 .Lrts_skip
	v_readlane_b32 s1, v255, 48
	s_cmp_lg_u32 s1, 2
	s_cbranch_scc1 .Lrts_known
	s_and_b32 s0, s91, 63
	s_lshl_b32 s0, s0, 2
	s_add_i32 s0, s0, 15104
	v_readlane_b32 s2, v251, 32
	v_readlane_b32 s3, v251, 33
	s_add_u32 s2, s2, s0
	s_addc_u32 s3, s3, 0
	v_mov_b32_e32 v1, 0
	global_load_dword v2, v1, s[2:3] sc1
	s_waitcnt vmcnt(0)
	v_readfirstlane_b32 s4, v2
	global_load_dword v2, v1, s[2:3] offset:256 sc1
	s_waitcnt vmcnt(0)
	v_readfirstlane_b32 s5, v2
	s_cmp_lg_u32 s4, s5
	s_cselect_b32 s1, 0, 1
	global_load_dword v2, v1, s[2:3] offset:512 sc1
	s_waitcnt vmcnt(0)
	v_readfirstlane_b32 s5, v2
	s_cmp_lg_u32 s4, s5
	s_cselect_b32 s1, 0, s1
	global_load_dword v2, v1, s[2:3] offset:768 sc1
	s_waitcnt vmcnt(0)
	v_readfirstlane_b32 s5, v2
	s_cmp_lg_u32 s4, s5
	s_cselect_b32 s1, 0, s1
	s_cmp_eq_u32 s4, 0
	s_cselect_b32 s1, 0, s1
	v_writelane_b32 v255, s1, 48
.Lrts_known:
	s_cmp_lg_u32 s1, 0
	s_cbranch_scc1 .Lrts_fast
	buffer_wbl2 sc1
	s_waitcnt vmcnt(0)
.Lrts_fast:
	s_and_b32 s0, s91, 7
	s_lshl_b32 s0, s0, 3
	s_bfe_u32 s1, s91, 0x30003
	s_add_i32 s0, s0, s1
	v_readlane_b32 s1, v255, 45
	s_lshl_b32 s1, s1, 6
	s_add_i32 s0, s0, s1
	s_lshl_b32 s0, s0, 2
	s_add_i32 s0, s0, 14080
	v_readlane_b32 s2, v251, 32
	v_readlane_b32 s3, v251, 33
	s_add_u32 s2, s2, s0
	s_addc_u32 s3, s3, 0
	s_mov_b64 s[4:5], exec
	s_mov_b64 exec, 1
	v_mov_b32_e32 v1, 0
	v_mov_b32_e32 v2, 1
	global_atomic_add v1, v2, s[2:3]
	s_mov_b64 exec, s[4:5]

.LBB0_962:
	v_mov_b32_e32 v228, v221
	v_mov_b32_e32 v221, 0x2000
	v_mov_b32_e32 v248, v250
	v_mov_b32_e32 v249, 0x160000
	s_barrier
	v_readlane_b32 s0, v251, 36
	s_cmp_lg_u32 s0, 0
	s_cbranch_scc1 .Lygcf_skip
	buffer_wbl2 sc1
	s_waitcnt vmcnt(0)
	v_readlane_b32 s0, v255, 45
	s_lshl_b32 s0, s0, 2
	s_add_i32 s0, s0, 14048
	v_readlane_b32 s2, v251, 32
	v_readlane_b32 s3, v251, 33
	s_add_u32 s2, s2, s0
	s_addc_u32 s3, s3, 0
	s_mov_b64 s[4:5], exec
	s_mov_b64 exec, 1
	v_mov_b32_e32 v1, 0
	v_mov_b32_e32 v2, 1
	global_atomic_add v1, v2, s[2:3]
	s_mov_b64 exec, s[4:5]
.Lygcf_skip:
.LBB0_963:
	v_readlane_b32 s0, v254, 9
	v_readlane_b32 s1, v254, 10
	s_andn2_b64 vcc, exec, s[0:1]
	s_cbranch_vccnz .LBB0_1032
	v_readlane_b32 s1, v251, 36
	s_waitcnt lgkmcnt(0)
	s_cmp_gt_u32 s26, 16
	s_cselect_b32 s0, 8, 0
	v_lshl_add_u32 v0, s1, 6, v220
	s_mov_b32 s1, s91
	s_cmp_lt_i32 s1, s0
	s_cbranch_scc1 .LBB0_1032

.LBB0_1053:
	s_waitcnt lgkmcnt(0)
	s_and_b32 s0, s91, 7
	s_lshl_b32 s0, s0, 3
	s_bfe_u32 s1, s91, 0x30003
	s_add_i32 s0, s0, s1
	v_readlane_b32 s1, v255, 45
	s_lshl_b32 s1, s1, 6
	s_add_i32 s0, s0, s1
	s_lshl_b32 s0, s0, 2
	s_add_i32 s0, s0, 14080
	v_readlane_b32 s2, v251, 32
	v_readlane_b32 s3, v251, 33
	s_add_u32 s2, s2, s0
	s_addc_u32 s3, s3, 0
	s_mov_b32 s12, 0
	v_mov_b32_e32 v5, 0
.Lgb7_spin:
	global_load_dword v1, v5, s[2:3] sc1
	s_waitcnt vmcnt(0)
	v_readfirstlane_b32 s9, v1
	s_cmp_ge_u32 s9, 4
	s_cbranch_scc1 .Lgb7_done
	s_sleep 1
	s_add_i32 s12, s12, 1
	s_cmp_lt_u32 s12, 0x100000
	s_cbranch_scc1 .Lgb7_spin

.LBB0_1090:
	v_readlane_b32 s0, v251, 36
	s_waitcnt lgkmcnt(0)
	v_readlane_b32 s26, v255, 49
	s_cmp_eq_u32 s26, 0
	s_cselect_b32 s26, s91, s26
	v_readlane_b32 s14, v252, 47
	s_waitcnt vmcnt(0)
	v_lshl_add_u32 v0, s0, 6, v220
	s_movk_i32 s0, 0x100
	s_cmp_lt_u32 s26, 0x100
	s_cbranch_scc1 .Loute_n
	s_add_i32 s0, s26, 1
.Loute_n:
	v_writelane_b32 v255, s0, 50
	s_cmp_ge_i32 s26, s0
	v_readfirstlane_b32 s27, v0
	v_readlane_b32 s15, v252, 48
	s_cbranch_scc1 .LBB0_1124
	s_cmpk_lt_i32 s26, 0x100
	s_mov_b64 s[0:1], -1
	s_cbranch_scc0 .LBB0_1097
	s_ashr_i32 s0, s26, 31
	s_lshr_b32 s0, s0, 29
	s_add_i32 s2, s26, s0
	s_and_b32 s0, s2, -8
	s_sub_i32 s3, s26, s0
	s_cmp_gt_i32 s3, -1
	s_mov_b64 s[0:1], -1
	s_cbranch_scc0 .LBB0_1094
	s_lshl_b32 s4, s3, 5
	s_mov_b64 s[0:1], 0

.LBB0_1105:
	s_load_dword s0, s[64:65], 0x0
	s_add_i32 s36, s36, 1
	s_mov_b32 s5, 16
	s_mov_b64 s[18:19], s[20:21]
	s_mov_b64 s[16:17], s[14:15]
	s_waitcnt lgkmcnt(0)
	s_mul_i32 s22, s36, s0
	s_add_i32 s22, s22, s26
	v_readlane_b32 s0, v255, 50
	s_cmp_ge_i32 s22, s0
	s_cselect_b64 s[0:1], -1, 0
	s_and_b64 vcc, exec, s[0:1]
	s_cbranch_vccnz .LBB0_1116
	s_cmpk_lt_i32 s22, 0x100
	s_mov_b64 s[6:7], -1
	s_cbranch_scc0 .LBB0_1112
	s_ashr_i32 s2, s22, 31
	s_lshr_b32 s2, s2, 29
	s_add_i32 s4, s22, s2
	s_and_b32 s2, s4, -8
	s_sub_i32 s5, s22, s2
	s_cmp_gt_i32 s5, -1
	s_mov_b64 s[2:3], -1
	s_cbranch_scc0 .LBB0_1109
	s_lshl_b32 s6, s5, 5
	s_mov_b64 s[2:3], 0

.LBB0_1124:
	v_readlane_b32 s0, v255, 49
	s_cmp_eq_u32 s0, 0
	s_cbranch_scc1 .Loutx_first
	s_mov_b32 s0, 0
	v_writelane_b32 v255, s0, 49
	s_branch .Loutx_done
.Loutx_first:
	s_sub_i32 s0, s91, 32
	s_cmp_gt_u32 s0, 31
	s_cbranch_scc1 .Loutx_done
	v_readlane_b32 s1, v254, 8
	s_cmpk_eq_i32 s1, 0x100
	s_cbranch_scc1 .Loutx_done
	s_addk_i32 s0, 0x100
	v_writelane_b32 v255, s0, 49
	v_readlane_b32 s0, v251, 36
	s_cmp_lg_u32 s0, 0
	s_cbranch_scc1 .Loutx_wait
	v_readlane_b32 s0, v255, 45
	s_lshl_b32 s0, s0, 2
	s_add_i32 s0, s0, 14048
	v_readlane_b32 s2, v251, 32
	v_readlane_b32 s3, v251, 33
	s_add_u32 s2, s2, s0
	s_addc_u32 s3, s3, 0
	s_mov_b32 s1, 0
	v_mov_b32_e32 v1, 0
.Loutx_poll:
	global_load_dword v2, v1, s[2:3] sc1
	s_waitcnt vmcnt(0)
	v_readfirstlane_b32 s0, v2
	s_cmp_ge_u32 s0, 8
	s_cbranch_scc1 .Loutx_wait
	s_sleep 2
	s_add_i32 s1, s1, 1
	s_cmp_lt_u32 s1, 40000
	s_cbranch_scc1 .Loutx_poll
.Loutx_wait:
	s_barrier
	buffer_inv sc1
	s_waitcnt vmcnt(0)
	s_branch .LBB0_1090
.Loutx_done:
	v_readlane_b32 s0, v252, 53
	s_add_i32 s0, s0, 8
	s_cmp_lt_i32 s0, s14
	s_cselect_b64 s[2:3], -1, 0
	s_cmp_ge_i32 s0, s15
	s_cselect_b64 s[4:5], -1, 0
	s_or_b64 s[2:3], s[2:3], s[4:5]
	s_and_b64 vcc, exec, s[2:3]
	s_cbranch_vccnz .LBB0_1203
	v_readlane_b32 s2, v252, 47
	s_cmp_le_i32 s0, s2
	s_mov_b64 s[68:69], 0x100000
	s_mov_b64 s[86:87], 0x100800
	v_readlane_b32 s3, v252, 48
	s_cbranch_scc1 .LBB0_1181
	s_waitcnt vmcnt(0)
	v_readlane_b32 s0, v251, 36
	s_waitcnt vmcnt(0) lgkmcnt(0)
	s_barrier
	s_nop 0
	v_lshl_add_u32 v0, s0, 6, v220
	s_nop 0
	v_cmp_eq_u32_e32 vcc, 0, v0
	s_and_saveexec_b64 s[62:63], vcc
	s_cbranch_execz .LBB0_1180
	v_readlane_b32 s1, v252, 35
	s_waitcnt vmcnt(0) expcnt(0) lgkmcnt(0)
	s_getreg_b32 s0, hwreg(HW_REG_XCC_ID, 0, 4)
	v_mov_b32_e32 v0, s1
	ds_read_b32 v2, v0
	v_readlane_b32 s1, v252, 36
	s_and_b32 s78, s0, 15
	s_waitcnt lgkmcnt(0)
	v_cmp_ne_u32_e32 vcc, 0, v2
	v_mov_b32_e32 v0, s1
	ds_read_b32 v0, v0
	s_cbranch_vccnz .LBB0_1144
	s_mov_b32 s6, 1
	s_branch .LBB0_1130
